# v35: v34 + attention item epilogue stores widened to dwordx4 via v_permlane32_swap pairs
# speedup vs baseline: 1.0024x; 1.0024x over previous
; __device__ __forceinline__ void phase_attn(const Frame& F, int l, bool last, int ai, int na) {
;     ...
;         const float inv = 1.0f / lrun;
;         f16* op = F.Z + (size_t)(qrow0 + r32) * ZLD + Z_AQ + hq * 128;
; #pragma unroll
;         for (int dt = 0; dt < 4; ++dt)
; #pragma unroll
;             for (int g4 = 0; g4 < 4; ++g4)
;                 *(u32x2*)(op + dt * 32 + g4 * 8 + hh * 4) = (u32x2){pk_f16(oacc[dt][g4 * 4] * inv, oacc[dt][g4 * 4 + 1] * inv), pk_f16(oacc[dt][g4 * 4 + 2] * inv, oacc[dt][g4 * 4 + 3] * inv)};
.LBB0_602:
	v_div_scale_f32 v0, s[2:3], v171, v171, 1.0
	v_rcp_f32_e32 v2, v0
	v_div_scale_f32 v3, vcc, 1.0, v171, 1.0
	s_add_i32 s17, s17, s56
	v_fma_f32 v4, -v0, v2, 1.0
	v_fmac_f32_e32 v2, v4, v2
	v_mul_f32_e32 v4, v3, v2
	v_fma_f32 v5, -v0, v4, v3
	v_fmac_f32_e32 v4, v5, v2
	v_fma_f32 v0, -v0, v4, v3
	v_div_fmas_f32 v0, v0, v2, v4
	v_div_fixup_f32 v6, v0, v171, 1.0
	v_mov_b32_e32 v13, v6
	v_lshlrev_b32_e32 v0, 2, v164
	v_lshl_add_u64 v[2:3], v[172:173], 0, v[0:1]
	v_mul_f32_e32 v0, v64, v13
	v_mul_f32_e32 v12, v65, v13
	v_cvt_pk_f16_f32 v4, v0, v12
	v_mul_f32_e32 v0, v66, v13
	v_mul_f32_e32 v12, v67, v13
	v_cvt_pk_f16_f32 v5, v0, v12
	v_mul_f32_e32 v0, v68, v13
	v_mul_f32_e32 v12, v69, v13
	v_cvt_pk_f16_f32 v6, v0, v12
	v_mul_f32_e32 v0, v70, v13
	v_mul_f32_e32 v12, v71, v13
	v_cvt_pk_f16_f32 v7, v0, v12
	s_nop 1
	v_permlane32_swap_b32_e32 v4, v6
	v_permlane32_swap_b32_e32 v5, v7
	global_store_dwordx4 v[2:3], v[4:7], off
	v_mul_f32_e32 v0, v72, v13
	v_mul_f32_e32 v12, v73, v13
	v_cvt_pk_f16_f32 v8, v0, v12
	v_mul_f32_e32 v0, v74, v13
	v_mul_f32_e32 v12, v75, v13
	v_cvt_pk_f16_f32 v9, v0, v12
	v_mul_f32_e32 v0, v76, v13
	v_mul_f32_e32 v12, v77, v13
	v_cvt_pk_f16_f32 v10, v0, v12
	v_mul_f32_e32 v0, v78, v13
	v_mul_f32_e32 v12, v79, v13
	v_cvt_pk_f16_f32 v11, v0, v12
	s_nop 1
	v_permlane32_swap_b32_e32 v8, v10
	v_permlane32_swap_b32_e32 v9, v11
	global_store_dwordx4 v[2:3], v[8:11], off offset:32
	v_mul_f32_e32 v0, v48, v13
	v_mul_f32_e32 v12, v49, v13
	v_cvt_pk_f16_f32 v4, v0, v12
	v_mul_f32_e32 v0, v50, v13
	v_mul_f32_e32 v12, v51, v13
	v_cvt_pk_f16_f32 v5, v0, v12
	v_mul_f32_e32 v0, v52, v13
	v_mul_f32_e32 v12, v53, v13
	v_cvt_pk_f16_f32 v6, v0, v12
	v_mul_f32_e32 v0, v54, v13
	v_mul_f32_e32 v12, v55, v13
	v_cvt_pk_f16_f32 v7, v0, v12
	s_nop 1
	v_permlane32_swap_b32_e32 v4, v6
	v_permlane32_swap_b32_e32 v5, v7
	global_store_dwordx4 v[2:3], v[4:7], off offset:64
	v_mul_f32_e32 v0, v56, v13
	v_mul_f32_e32 v12, v57, v13
	v_cvt_pk_f16_f32 v8, v0, v12
	v_mul_f32_e32 v0, v58, v13
	v_mul_f32_e32 v12, v59, v13
	v_cvt_pk_f16_f32 v9, v0, v12
	v_mul_f32_e32 v0, v60, v13
	v_mul_f32_e32 v12, v61, v13
	v_cvt_pk_f16_f32 v10, v0, v12
	v_mul_f32_e32 v0, v62, v13
	v_mul_f32_e32 v12, v63, v13
	v_cvt_pk_f16_f32 v11, v0, v12
	s_nop 1
	v_permlane32_swap_b32_e32 v8, v10
	v_permlane32_swap_b32_e32 v9, v11
	global_store_dwordx4 v[2:3], v[8:11], off offset:96
	v_mul_f32_e32 v0, v32, v13
	v_mul_f32_e32 v12, v33, v13
	v_cvt_pk_f16_f32 v4, v0, v12
	v_mul_f32_e32 v0, v34, v13
	v_mul_f32_e32 v12, v35, v13
	v_cvt_pk_f16_f32 v5, v0, v12
	v_mul_f32_e32 v0, v36, v13
	v_mul_f32_e32 v12, v37, v13
	v_cvt_pk_f16_f32 v6, v0, v12
	v_mul_f32_e32 v0, v38, v13
	v_mul_f32_e32 v12, v39, v13
	v_cvt_pk_f16_f32 v7, v0, v12
	s_nop 1
	v_permlane32_swap_b32_e32 v4, v6
	v_permlane32_swap_b32_e32 v5, v7
	global_store_dwordx4 v[2:3], v[4:7], off offset:128
	v_mul_f32_e32 v0, v40, v13
	v_mul_f32_e32 v12, v41, v13
	v_cvt_pk_f16_f32 v8, v0, v12
	v_mul_f32_e32 v0, v42, v13
	v_mul_f32_e32 v12, v43, v13
	v_cvt_pk_f16_f32 v9, v0, v12
	v_mul_f32_e32 v0, v44, v13
	v_mul_f32_e32 v12, v45, v13
	v_cvt_pk_f16_f32 v10, v0, v12
	v_mul_f32_e32 v0, v46, v13
	v_mul_f32_e32 v12, v47, v13
	v_cvt_pk_f16_f32 v11, v0, v12
	s_nop 1
	v_permlane32_swap_b32_e32 v8, v10
	v_permlane32_swap_b32_e32 v9, v11
	global_store_dwordx4 v[2:3], v[8:11], off offset:160
	v_mul_f32_e32 v0, v16, v13
	v_mul_f32_e32 v12, v17, v13
	v_cvt_pk_f16_f32 v4, v0, v12
	v_mul_f32_e32 v0, v18, v13
	v_mul_f32_e32 v12, v19, v13
	v_cvt_pk_f16_f32 v5, v0, v12
	v_mul_f32_e32 v0, v20, v13
	v_mul_f32_e32 v12, v21, v13
	v_cvt_pk_f16_f32 v6, v0, v12
	v_mul_f32_e32 v0, v22, v13
	v_mul_f32_e32 v12, v23, v13
	v_cvt_pk_f16_f32 v7, v0, v12
	s_nop 1
	v_permlane32_swap_b32_e32 v4, v6
	v_permlane32_swap_b32_e32 v5, v7
	global_store_dwordx4 v[2:3], v[4:7], off offset:192
	v_mul_f32_e32 v0, v24, v13
	v_mul_f32_e32 v12, v25, v13
	v_cvt_pk_f16_f32 v8, v0, v12
	v_mul_f32_e32 v0, v26, v13
	v_mul_f32_e32 v12, v27, v13
	v_cvt_pk_f16_f32 v9, v0, v12
	v_mul_f32_e32 v0, v28, v13
	v_mul_f32_e32 v12, v29, v13
	v_cvt_pk_f16_f32 v10, v0, v12
	v_mul_f32_e32 v0, v30, v13
	v_mul_f32_e32 v12, v31, v13
	v_cvt_pk_f16_f32 v11, v0, v12
	s_nop 1
	v_permlane32_swap_b32_e32 v8, v10
	v_permlane32_swap_b32_e32 v9, v11
	s_movk_i32 s36, 0x1000
	s_cmp_ge_i32 s17, s0
	global_store_dwordx4 v[2:3], v[8:11], off offset:224
	s_cbranch_scc1 .LBB0_620
